# MLA attention QK: K fragments read six ahead into spare registers with counted lgkm waits (on top of lazy rescale + permlane)
# speedup vs baseline: 1.0076x; 1.0076x over previous
.LBB0_685:
	v_lshl_or_b32 v0, s38, 5, v202
	v_mad_u32_u24 v0, v0, s30, v208
	ds_read_b128 v[2:5], v0
	ds_read_b128 v[6:9], v0 offset:32
	ds_read_b128 v[222:225], v0 offset:64
	ds_read_b128 v[226:229], v0 offset:96
	ds_read_b128 v[230:233], v0 offset:128
	ds_read_b128 v[234:237], v0 offset:160
	s_waitcnt lgkmcnt(5)
	v_mfma_f32_32x32x16_bf16 v[80:95], v[2:5], v[148:151], 0
	ds_read_b128 v[2:5], v0 offset:192
	s_waitcnt lgkmcnt(5)
	v_mfma_f32_32x32x16_bf16 v[80:95], v[6:9], v[96:99], v[80:95]
	ds_read_b128 v[6:9], v0 offset:224
	s_waitcnt lgkmcnt(5)
	v_mfma_f32_32x32x16_bf16 v[80:95], v[222:225], v[100:103], v[80:95]
	ds_read_b128 v[222:225], v0 offset:256
	s_waitcnt lgkmcnt(5)
	v_mfma_f32_32x32x16_bf16 v[80:95], v[226:229], v[104:107], v[80:95]
	ds_read_b128 v[226:229], v0 offset:288
	s_waitcnt lgkmcnt(5)
	v_mfma_f32_32x32x16_bf16 v[80:95], v[230:233], v[108:111], v[80:95]
	ds_read_b128 v[230:233], v0 offset:320
	s_waitcnt lgkmcnt(5)
	v_mfma_f32_32x32x16_bf16 v[80:95], v[234:237], v[112:115], v[80:95]
	ds_read_b128 v[234:237], v0 offset:352
	s_waitcnt lgkmcnt(5)
	v_mfma_f32_32x32x16_bf16 v[80:95], v[2:5], v[116:119], v[80:95]
	s_waitcnt lgkmcnt(4)
	v_mfma_f32_32x32x16_bf16 v[80:95], v[6:9], v[120:123], v[80:95]
	s_waitcnt lgkmcnt(3)
	v_mfma_f32_32x32x16_bf16 v[80:95], v[222:225], v[124:127], v[80:95]
	s_waitcnt lgkmcnt(2)
	v_mfma_f32_32x32x16_bf16 v[80:95], v[226:229], v[128:131], v[80:95]
	s_waitcnt lgkmcnt(1)
	v_mfma_f32_32x32x16_bf16 v[80:95], v[230:233], v[132:135], v[80:95]
	s_waitcnt lgkmcnt(0)
	v_mfma_f32_32x32x16_bf16 v[80:95], v[234:237], v[140:143], v[80:95]
	s_nop 11
	v_max_f32_e32 v0, v81, v81
	v_max_f32_e32 v2, v80, v80
	v_max_f32_e32 v0, v2, v0
	v_max3_f32 v0, v0, v82, v83
	v_max3_f32 v0, v0, v84, v85
	v_max3_f32 v0, v0, v86, v87
	v_max3_f32 v0, v0, v88, v89
	v_max3_f32 v0, v0, v90, v91
	v_max3_f32 v0, v0, v92, v93
	v_max3_f32 v0, v0, v94, v95
	v_mov_b32_e32 v2, v0
	s_nop 1
	v_permlane32_swap_b32_e32 v2, v0
	s_waitcnt lgkmcnt(0)
	v_max_f32_e32 v2, v2, v2
	v_max_f32_e32 v0, v0, v2
	v_mul_f32_e32 v0, 0x3dd53b94, v0
	v_add_f32_e32 v250, 0xc1000000, v0
	v_cmp_gt_f32_e32 vcc, v250, v198
	s_cbranch_vccz .LBB0_684
	v_max_f32_e32 v0, v0, v0
	v_max_f32_e32 v2, v198, v198
	v_max_f32_e32 v2, v2, v0
	v_sub_f32_e32 v0, v198, v2
	v_exp_f32_e32 v0, v0
	v_mov_b32_e32 v198, v2
	v_pk_mul_f32 v[78:79], v[78:79], v[0:1] op_sel_hi:[1,0]
	v_pk_mul_f32 v[76:77], v[76:77], v[0:1] op_sel_hi:[1,0]
	v_pk_mul_f32 v[74:75], v[74:75], v[0:1] op_sel_hi:[1,0]
	v_pk_mul_f32 v[72:73], v[72:73], v[0:1] op_sel_hi:[1,0]
	v_pk_mul_f32 v[70:71], v[70:71], v[0:1] op_sel_hi:[1,0]
	v_pk_mul_f32 v[68:69], v[68:69], v[0:1] op_sel_hi:[1,0]
	v_pk_mul_f32 v[66:67], v[66:67], v[0:1] op_sel_hi:[1,0]
	v_pk_mul_f32 v[64:65], v[64:65], v[0:1] op_sel_hi:[1,0]
	v_pk_mul_f32 v[62:63], v[62:63], v[0:1] op_sel_hi:[1,0]
	v_pk_mul_f32 v[60:61], v[60:61], v[0:1] op_sel_hi:[1,0]
	v_pk_mul_f32 v[58:59], v[58:59], v[0:1] op_sel_hi:[1,0]
	v_pk_mul_f32 v[56:57], v[56:57], v[0:1] op_sel_hi:[1,0]
	v_pk_mul_f32 v[54:55], v[54:55], v[0:1] op_sel_hi:[1,0]
	v_pk_mul_f32 v[52:53], v[52:53], v[0:1] op_sel_hi:[1,0]
	v_pk_mul_f32 v[50:51], v[50:51], v[0:1] op_sel_hi:[1,0]
	v_pk_mul_f32 v[48:49], v[48:49], v[0:1] op_sel_hi:[1,0]
	v_pk_mul_f32 v[46:47], v[46:47], v[0:1] op_sel_hi:[1,0]
	v_pk_mul_f32 v[44:45], v[44:45], v[0:1] op_sel_hi:[1,0]
	v_pk_mul_f32 v[42:43], v[42:43], v[0:1] op_sel_hi:[1,0]
	v_pk_mul_f32 v[40:41], v[40:41], v[0:1] op_sel_hi:[1,0]
	v_pk_mul_f32 v[38:39], v[38:39], v[0:1] op_sel_hi:[1,0]
	v_pk_mul_f32 v[36:37], v[36:37], v[0:1] op_sel_hi:[1,0]
	v_pk_mul_f32 v[34:35], v[34:35], v[0:1] op_sel_hi:[1,0]
	v_pk_mul_f32 v[32:33], v[32:33], v[0:1] op_sel_hi:[1,0]
	v_pk_mul_f32 v[30:31], v[30:31], v[0:1] op_sel_hi:[1,0]
	v_pk_mul_f32 v[28:29], v[28:29], v[0:1] op_sel_hi:[1,0]
	v_pk_mul_f32 v[26:27], v[26:27], v[0:1] op_sel_hi:[1,0]
	v_pk_mul_f32 v[24:25], v[24:25], v[0:1] op_sel_hi:[1,0]
	v_pk_mul_f32 v[22:23], v[22:23], v[0:1] op_sel_hi:[1,0]
	v_pk_mul_f32 v[20:21], v[20:21], v[0:1] op_sel_hi:[1,0]
	v_pk_mul_f32 v[18:19], v[18:19], v[0:1] op_sel_hi:[1,0]
	v_pk_mul_f32 v[16:17], v[16:17], v[0:1] op_sel_hi:[1,0]
	v_mul_f32_e32 v193, v193, v0
	s_branch .LBB0_684
